# attention ring-stage registers hold byte offsets (per-use shifts removed)
# speedup vs baseline: 1.0339x; 1.0035x over previous
.Ltb_u1_b:
	s_ashr_i32 s11, s6, 6
	s_lshl_b32 s10, s43, 4
	s_lshl_b32 s26, s11, 2
	v_bfe_u32 v233, v237, 4, 2
	s_and_b32 s60, s10, 0xfffff000
	v_or_b32_e32 v52, s26, v233
	s_waitcnt vmcnt(0)
	v_add_u32_e32 v2, s60, v52
	v_ashrrev_i32_e32 v3, 31, v2
	v_readlane_b32 s18, v252, 31
	v_bitop3_b32 v0, s26, v237, v233 bitop3:0x36
	v_lshlrev_b64 v[2:3], 12, v[2:3]
	v_readlane_b32 s19, v252, 32
	s_and_b32 s46, s43, 15
	s_lshl_b32 s84, s28, 8
	v_lshl_add_u64 v[2:3], s[18:19], 0, v[2:3]
	v_lshlrev_b32_e32 v0, 4, v0
	s_xor_b32 s17, s46, 31
	s_and_b32 s2, s11, 3
	v_lshl_add_u64 v[2:3], v[2:3], 0, s[84:85]
	v_and_b32_e32 v0, 0xf0, v0
	s_lshl_b32 s27, s11, 3
	v_bfe_u32 v53, v237, 3, 3
	s_lshl_b32 s21, s17, 7
	s_lshl_b32 s22, s2, 5
	s_lshl_b32 s18, s28, 7
	v_lshl_add_u64 v[2:3], v[2:3], 0, v[0:1]
	v_or_b32_e32 v0, s27, v53
	s_or_b32 s20, s22, s21
	v_lshrrev_b32_e32 v54, 1, v0
	v_add_u32_e32 v4, s18, v0
	v_and_b32_e32 v235, 31, v237
	v_xor_b32_e32 v6, v54, v237
	v_ashrrev_i32_e32 v5, 31, v4
	v_readlane_b32 s36, v252, 39
	s_or_b32 s10, s20, s60
	v_lshlrev_b64 v[4:5], 15, v[4:5]
	v_readlane_b32 s37, v252, 40
	v_lshlrev_b32_e32 v0, 4, v6
	v_or_b32_e32 v6, s10, v235
	v_lshl_add_u64 v[4:5], s[36:37], 0, v[4:5]
	v_ashrrev_i32_e32 v7, 31, v6
	v_readlane_b32 s36, v252, 17
	s_ashr_i32 s3, s6, 8
	v_lshlrev_b64 v[6:7], 12, v[6:7]
	v_readlane_b32 s37, v252, 18
	s_ashr_i32 s61, s60, 31
	v_bfe_u32 v234, v237, 5, 1
	v_lshl_add_u64 v[6:7], s[36:37], 0, v[6:7]
	s_lshl_b32 s36, s3, 6
	v_lshl_add_u64 v[4:5], s[60:61], 1, v[4:5]
	v_and_b32_e32 v0, 0x70, v0
	v_lshl_add_u64 v[6:7], v[6:7], 0, s[84:85]
	s_ashr_i32 s37, s36, 31
	v_lshl_add_u64 v[4:5], v[4:5], 0, v[0:1]
	v_lshl_add_u64 v[6:7], s[36:37], 1, v[6:7]
	v_lshlrev_b32_e32 v0, 4, v234
	v_lshl_add_u64 v[6:7], v[6:7], 0, v[0:1]
	global_load_dwordx4 v[146:149], v[6:7], off nt
	global_load_dwordx4 v[150:153], v[6:7], off offset:32 nt
	global_load_dwordx4 v[154:157], v[6:7], off offset:64 nt
	global_load_dwordx4 v[158:161], v[6:7], off offset:96 nt
	s_lshl_b32 s11, s11, 10
	s_add_i32 s11, s11, 0
	s_mov_b32 m0, s11
	s_mov_b64 s[36:37], 0x20000
	global_load_lds_dwordx4 v[2:3], off
	v_lshl_add_u64 v[8:9], v[2:3], 0, s[36:37]
	s_add_i32 m0, s11, 0x2000
	s_mov_b64 s[36:37], 0x40000
	global_load_lds_dwordx4 v[8:9], off
	s_add_i32 m0, s11, 0x4000
	v_lshl_add_u64 v[8:9], v[2:3], 0, s[36:37]
	s_mov_b64 s[36:37], 0x60000
	global_load_lds_dwordx4 v[8:9], off
	v_lshl_add_u64 v[8:9], v[2:3], 0, s[36:37]
	s_add_i32 m0, s11, 0x6000
	s_mov_b64 s[36:37], 0x200000
	global_load_lds_dwordx4 v[8:9], off
	s_add_i32 m0, s11, 0xc000
	v_lshl_add_u64 v[8:9], v[4:5], 0, s[36:37]
	global_load_lds_dwordx4 v[4:5], off
	s_add_i32 m0, s11, 0xe000
	s_mov_b64 s[36:37], 0xa0000
	global_load_lds_dwordx4 v[8:9], off
	s_add_i32 m0, s11, 0x8000
	v_lshl_add_u64 v[8:9], v[2:3], 0, s[34:35]
	global_load_lds_dwordx4 v[8:9], off
	v_lshl_add_u64 v[2:3], v[2:3], 0, s[36:37]
	s_add_i32 m0, s11, 0xa000
	s_mov_b64 s[36:37], 0x80
	global_load_lds_dwordx4 v[2:3], off
	s_add_i32 m0, s11, 0x10000
	v_lshl_add_u64 v[2:3], v[4:5], 0, s[36:37]
	s_mov_b64 s[36:37], 0x200080
	global_load_lds_dwordx4 v[2:3], off
	v_lshl_add_u64 v[2:3], v[4:5], 0, s[36:37]
	s_add_i32 m0, s11, 0x12000
	v_and_b32_e32 v0, 19, v237
	global_load_lds_dwordx4 v[2:3], off
	v_lshlrev_b32_e32 v2, 1, v237
	v_lshrrev_b32_e32 v35, 1, v34
	v_and_or_b32 v0, v2, 8, v0
	v_and_b32_e32 v22, 4, v35
	v_or_b32_e32 v2, v0, v22
	v_lshl_or_b32 v45, s3, 3, v234
	v_lshlrev_b32_e32 v44, 8, v2
	v_bitop3_b32 v2, v2, v45, 15 bitop3:0x6c
	v_lshl_add_u32 v239, v2, 4, v44
	s_waitcnt vmcnt(4)
	s_barrier
	v_add_u32_e32 v6, 0, v239
	v_bitop3_b32 v0, v0, 15, v22 bitop3:0xc8
	ds_read_b128 v[2:5], v6
	ds_read_b128 v[18:21], v6 offset:8192
	v_bitop3_b32 v22, v45, v0, 2 bitop3:0x36
	v_lshl_add_u32 v240, v22, 4, v44
	v_add_u32_e32 v40, 0, v240
	ds_read_b128 v[36:39], v40
	s_waitcnt vmcnt(0) lgkmcnt(0)
	v_mfma_f32_32x32x16_bf16 v[2:17], v[2:5], v[146:149], 0
	ds_read_b128 v[40:43], v40 offset:8192
	v_bfe_u32 v34, v34, 1, 3
	v_bitop3_b32 v57, v234, v34, 2 bitop3:0x36
	v_bitop3_b32 v58, v234, v34, 4 bitop3:0x36
	v_bitop3_b32 v59, v234, v34, 6 bitop3:0x36
	s_and_b32 s56, s42, 0xfffff000
	s_add_i32 s26, s26, s56
	v_mfma_f32_32x32x16_bf16 v[18:33], v[18:21], v[146:149], 0
	s_lshr_b32 s16, s43, 4
	s_and_b32 s16, s16, 15
	s_lshl_b32 s36, s16, 7
	s_lshl_b32 s37, s16, 8
	s_add_i32 s27, s27, s36
	s_ashr_i32 s57, s56, 31
	s_lshl_b64 s[44:45], s[56:57], 1
	v_mfma_f32_32x32x16_bf16 v[2:17], v[36:39], v[150:153], v[2:17]
	v_bitop3_b32 v36, v45, v0, 4 bitop3:0x36
	v_lshl_add_u32 v241, v36, 4, v44
	v_add_u32_e32 v46, 0, v241
	ds_read_b128 v[36:39], v46
	v_bitop3_b32 v0, v45, v0, 6 bitop3:0x36
	v_lshl_add_u32 v243, v0, 4, v44
	v_add_u32_e32 v0, 0, v243
	s_waitcnt lgkmcnt(1)
	v_mfma_f32_32x32x16_bf16 v[18:33], v[40:43], v[150:153], v[18:33]
	ds_read_b128 v[40:43], v46 offset:8192
	v_lshlrev_b32_e32 v236, 3, v234
	s_mov_b32 s84, s85
	v_bitop3_b32 v56, v35, v234, 7 bitop3:0x6c
	s_mov_b32 s86, s85
	s_mov_b32 s87, s85
	s_mov_b32 s88, s85
	s_waitcnt lgkmcnt(1)
	v_mfma_f32_32x32x16_bf16 v[2:17], v[36:39], v[154:157], v[2:17]
	ds_read_b128 v[36:39], v0
	s_mov_b32 s89, s85
	s_mov_b32 s90, s85
	s_mov_b32 s91, s85
	s_mov_b32 s92, s85
	s_mov_b32 s93, s85
	s_mov_b32 s94, s85
	s_waitcnt lgkmcnt(1)
	v_mfma_f32_32x32x16_bf16 v[18:33], v[40:43], v[154:157], v[18:33]
	ds_read_b128 v[40:43], v0 offset:8192
	s_mov_b32 s95, s85
	s_mov_b32 s96, s85
	s_mov_b32 s97, s85
	s_mov_b32 s98, s85
	s_mov_b32 s99, s85
	s_lshl_b32 s16, s17, 1
	s_waitcnt lgkmcnt(1)
	v_mfma_f32_32x32x16_bf16 v[2:17], v[36:39], v[158:161], v[2:17]
	v_lshlrev_b32_e32 v55, 7, v235
	s_lshr_b32 s19, s20, 6
	s_add_i32 s17, s16, 2
	s_add_i32 s19, s19, 1
	v_lshl_or_b32 v244, v56, 4, v55
	v_lshl_or_b32 v245, v57, 4, v55
	v_lshl_or_b32 v246, v58, 4, v55
	s_waitcnt lgkmcnt(0)
	v_mfma_f32_32x32x16_bf16 v[18:33], v[40:43], v[158:161], v[18:33]
	s_nop 2
	v_max_f32_e32 v34, v3, v3
	v_lshl_or_b32 v247, v59, 4, v55
	s_mov_b32 s23, 1
	v_and_b32_e32 v238, 63, v237
	s_mov_b32 s31, 0x8000
	s_min_u32 s19, s17, s19
	s_addk_i32 s20, 0xff50
	s_nop 1
	v_max_f32_e32 v0, v19, v19
	v_max_f32_e32 v0, v34, v0
	v_max3_f32 v0, v2, v18, v0
	v_max3_f32 v34, v20, v5, v21
	v_max3_f32 v0, v0, v4, v34
	v_max3_f32 v34, v22, v7, v23
	v_max3_f32 v0, v0, v6, v34
	v_max3_f32 v34, v24, v9, v25
	v_max3_f32 v0, v0, v8, v34
	v_max3_f32 v34, v26, v11, v27
	v_max3_f32 v0, v0, v10, v34
	v_max3_f32 v34, v28, v13, v29
	v_max3_f32 v0, v0, v12, v34
	v_max3_f32 v34, v30, v15, v31
	v_max3_f32 v0, v0, v14, v34
	v_max3_f32 v34, v32, v17, v33
	v_max3_f32 v0, v0, v16, v34
	v_mov_b32_e32 v34, v0
	s_nop 1
	v_permlane32_swap_b32_e32 v0, v34
	v_max_f32_e32 v34, v34, v34
	v_max_f32_e32 v0, v0, v0
	v_max_f32_e32 v213, v0, v34
	v_sub_f32_e32 v0, v2, v213
	v_exp_f32_e32 v60, v0
	v_sub_f32_e32 v0, v18, v213
	v_exp_f32_e32 v61, v0
	v_sub_f32_e32 v0, v3, v213
	v_sub_f32_e32 v2, v19, v213
	v_exp_f32_e32 v0, v0
	v_exp_f32_e32 v2, v2
	v_add_f32_e32 v3, v61, v60
	v_mov_b64_e32 v[34:35], s[84:85]
	v_cvt_pk_bf16_f32 v162, v60, v0
	v_pk_add_f32 v[18:19], v[2:3], v[0:1]
	v_sub_f32_e32 v3, v4, v213
	v_sub_f32_e32 v4, v20, v213
	v_pk_add_f32 v[18:19], v[18:19], v[18:19] op_sel_hi:[0,1]
	v_exp_f32_e32 v62, v4
	v_sub_f32_e32 v4, v5, v213
	v_exp_f32_e32 v3, v3
	v_exp_f32_e32 v18, v4
	v_sub_f32_e32 v4, v21, v213
	v_exp_f32_e32 v4, v4
	v_add_f32_e32 v5, v62, v3
	v_sub_u32_e32 v0, 7, v237
	v_cvt_pk_bf16_f32 v178, v61, v2
	v_pk_add_f32 v[20:21], v[4:5], v[18:19]
	v_sub_f32_e32 v5, v6, v213
	v_sub_f32_e32 v6, v22, v213
	v_pk_add_f32 v[20:21], v[20:21], v[20:21] op_sel_hi:[0,1]
	v_exp_f32_e32 v19, v6
	v_sub_f32_e32 v6, v7, v213
	v_exp_f32_e32 v5, v5
	v_exp_f32_e32 v20, v6
	v_sub_f32_e32 v6, v23, v213
	v_exp_f32_e32 v6, v6
	v_add_f32_e32 v7, v19, v5
	v_and_b32_e32 v0, 3, v0
	v_mov_b32_e32 v2, s33
	v_pk_add_f32 v[22:23], v[6:7], v[20:21]
	v_sub_f32_e32 v7, v8, v213
	v_sub_f32_e32 v8, v24, v213
	v_pk_add_f32 v[22:23], v[22:23], v[22:23] op_sel_hi:[0,1]
	v_exp_f32_e32 v21, v8
	v_sub_f32_e32 v8, v9, v213
	v_exp_f32_e32 v7, v7
	v_exp_f32_e32 v22, v8
	v_sub_f32_e32 v8, v25, v213
	v_exp_f32_e32 v8, v8
	v_add_f32_e32 v9, v21, v7
	s_movk_i32 s33, 0x510
	v_mad_u32_u24 v0, v0, s33, v2
	v_pk_add_f32 v[24:25], v[8:9], v[22:23]
	v_sub_f32_e32 v9, v10, v213
	v_sub_f32_e32 v10, v26, v213
	v_pk_add_f32 v[24:25], v[24:25], v[24:25] op_sel_hi:[0,1]
	v_exp_f32_e32 v23, v10
	v_sub_f32_e32 v10, v11, v213
	v_exp_f32_e32 v9, v9
	v_exp_f32_e32 v24, v10
	v_sub_f32_e32 v10, v27, v213
	v_exp_f32_e32 v10, v10
	v_add_f32_e32 v11, v23, v9
	v_or_b32_e32 v2, s26, v233
	v_cvt_pk_bf16_f32 v163, v3, v18
	v_pk_add_f32 v[26:27], v[10:11], v[24:25]
	v_sub_f32_e32 v11, v12, v213
	v_sub_f32_e32 v12, v28, v213
	v_pk_add_f32 v[26:27], v[26:27], v[26:27] op_sel_hi:[0,1]
	v_exp_f32_e32 v25, v12
	v_sub_f32_e32 v12, v13, v213
	v_exp_f32_e32 v11, v11
	v_exp_f32_e32 v26, v12
	v_sub_f32_e32 v12, v29, v213
	v_exp_f32_e32 v12, v12
	v_add_f32_e32 v13, v25, v11
	v_ashrrev_i32_e32 v3, 31, v2
	v_lshlrev_b64 v[214:215], 12, v[2:3]
	v_pk_add_f32 v[28:29], v[12:13], v[26:27]
	v_sub_f32_e32 v13, v14, v213
	v_sub_f32_e32 v14, v30, v213
	v_pk_add_f32 v[28:29], v[28:29], v[28:29] op_sel_hi:[0,1]
	v_exp_f32_e32 v27, v14
	v_sub_f32_e32 v14, v15, v213
	v_exp_f32_e32 v13, v13
	v_exp_f32_e32 v28, v14
	v_sub_f32_e32 v14, v31, v213
	v_exp_f32_e32 v14, v14
	v_sub_f32_e32 v15, v16, v213
	v_exp_f32_e32 v63, v15
	v_sub_f32_e32 v15, v32, v213
	v_exp_f32_e32 v32, v15
	v_add_f32_e32 v15, v27, v13
	v_pk_add_f32 v[30:31], v[14:15], v[28:29]
	v_bitop3_b32 v2, v52, 15, v237 bitop3:0x48
	v_pk_add_f32 v[30:31], v[30:31], v[30:31] op_sel_hi:[0,1]
	v_sub_f32_e32 v15, v17, v213
	v_lshlrev_b32_e32 v2, 4, v2
	v_exp_f32_e32 v30, v15
	v_sub_f32_e32 v15, v33, v213
	v_or3_b32 v214, v214, s37, v2
	v_or_b32_e32 v2, s27, v53
	v_exp_f32_e32 v50, v15
	v_ashrrev_i32_e32 v3, 31, v2
	v_cvt_pk_bf16_f32 v179, v62, v4
	v_lshlrev_b64 v[2:3], 15, v[2:3]
	v_bitop3_b32 v4, v54, 7, v237 bitop3:0x48
	v_lshl_or_b32 v2, v4, 4, v2
	v_add_f32_e32 v51, v32, v63
	v_lshl_add_u64 v[216:217], v[2:3], 0, s[44:45]
	v_sub_u32_e32 v2, v236, v235
	v_mov_b64_e32 v[48:49], s[98:99]
	v_pk_add_f32 v[16:17], v[50:51], v[30:31]
	v_subrev_u32_e32 v2, s22, v2
	v_mov_b64_e32 v[36:37], s[86:87]
	v_mov_b64_e32 v[38:39], s[88:89]
	v_mov_b64_e32 v[40:41], s[90:91]
	v_mov_b64_e32 v[42:43], s[92:93]
	v_mov_b64_e32 v[44:45], s[94:95]
	v_mov_b64_e32 v[46:47], s[96:97]
	v_xor_b32_e32 v66, 0x80000000, v213
	v_add_f32_e32 v242, v16, v17
	v_cvt_pk_bf16_f32 v164, v5, v20
	v_cvt_pk_bf16_f32 v165, v7, v22
	v_cvt_pk_bf16_f32 v170, v9, v24
	v_cvt_pk_bf16_f32 v171, v11, v26
	v_cvt_pk_bf16_f32 v172, v13, v28
	v_cvt_pk_bf16_f32 v173, v63, v30
	v_cvt_pk_bf16_f32 v180, v19, v6
	v_cvt_pk_bf16_f32 v181, v21, v8
	v_cvt_pk_bf16_f32 v186, v23, v10
	v_cvt_pk_bf16_f32 v187, v25, v12
	v_cvt_pk_bf16_f32 v188, v27, v14
	v_cvt_pk_bf16_f32 v189, v32, v50
	v_subrev_u32_e32 v248, s21, v2
	v_mov_b64_e32 v[64:65], v[48:49]
	v_mov_b64_e32 v[18:19], v[34:35]
	v_mov_b64_e32 v[2:3], v[34:35]
	v_readlane_b32 s94, v255, 10
	v_readlane_b32 s90, v255, 12
	v_mov_b32_e32 v67, v66
	v_mov_b32_e32 v68, v66
	v_mov_b32_e32 v69, v66
	v_mov_b32_e32 v70, v66
	v_mov_b32_e32 v71, v66
	v_mov_b32_e32 v72, v66
	v_mov_b32_e32 v73, v66
	v_mov_b32_e32 v74, v66
	v_mov_b32_e32 v75, v66
	v_mov_b32_e32 v76, v66
	v_mov_b32_e32 v77, v66
	v_mov_b32_e32 v78, v66
	v_mov_b32_e32 v79, v66
	v_mov_b32_e32 v80, v66
	v_mov_b32_e32 v81, v66
	s_mov_b32 s21, 0
	v_mov_b32_e32 v166, 0
	v_mov_b32_e32 v167, 0
	v_mov_b32_e32 v168, 0
	v_mov_b32_e32 v169, 0
	v_mov_b32_e32 v174, 0
	v_mov_b32_e32 v175, 0
	v_mov_b32_e32 v176, 0
	v_mov_b32_e32 v177, 0
	v_mov_b32_e32 v182, 0
	v_mov_b32_e32 v183, 0
	v_mov_b32_e32 v184, 0
	v_mov_b32_e32 v185, 0
	v_mov_b32_e32 v190, 0
	v_mov_b32_e32 v191, 0
	v_mov_b32_e32 v192, 0
	v_mov_b32_e32 v193, 0
	v_mov_b64_e32 v[62:63], v[46:47]
	v_mov_b64_e32 v[60:61], v[44:45]
	v_mov_b64_e32 v[58:59], v[42:43]
	v_mov_b64_e32 v[56:57], v[40:41]
	v_mov_b64_e32 v[54:55], v[38:39]
	v_mov_b64_e32 v[52:53], v[36:37]
	v_mov_b64_e32 v[50:51], v[34:35]
	v_mov_b64_e32 v[20:21], v[36:37]
	v_mov_b64_e32 v[22:23], v[38:39]
	v_mov_b64_e32 v[24:25], v[40:41]
	v_mov_b64_e32 v[26:27], v[42:43]
	v_mov_b64_e32 v[28:29], v[44:45]
	v_mov_b64_e32 v[30:31], v[46:47]
	v_mov_b64_e32 v[32:33], v[48:49]
	v_mov_b64_e32 v[4:5], v[36:37]
	v_mov_b64_e32 v[6:7], v[38:39]
	v_mov_b64_e32 v[8:9], v[40:41]
	v_mov_b64_e32 v[10:11], v[42:43]
	v_mov_b64_e32 v[12:13], v[44:45]
	v_mov_b64_e32 v[14:15], v[46:47]
	v_mov_b64_e32 v[16:17], v[48:49]
	s_mov_b32 s33, 0x4000
	s_mov_b32 s48, 0
	s_mov_b32 s49, 0
	s_movk_i32 s92, 0x6e
	s_movk_i32 s93, 0xd0
	s_mov_b32 s57, 0x41000000
	v_readlane_b32 s95, v255, 11
	v_readlane_b32 s91, v255, 13
	s_add_u32 s80, s8, 0xd0c0000
	s_addc_u32 s81, s9, 0
	s_add_u32 s62, s8, 0xd0e0000
	s_addc_u32 s63, s9, 0
	s_add_u32 s96, s8, 0x15000100
	s_addc_u32 s97, s9, 0
	s_add_u32 s58, s8, 0x15200100
	s_addc_u32 s59, s9, 0
	s_add_u32 s50, s8, 0xd100000
	s_addc_u32 s51, s9, 0
	s_add_u32 s4, s8, 0xd120000
	s_addc_u32 s5, s9, 0
	s_add_u32 s0, s8, 0x15000180
	s_addc_u32 s1, s9, 0
	s_add_u32 s52, s8, 0x15200180
	s_addc_u32 s53, s9, 0

.LBB0_168:
	v_add_u32_e32 v82, s33, v239
	v_add_u32_e32 v102, s33, v240
	ds_read_b128 v[98:101], v82
	ds_read_b128 v[114:117], v82 offset:8192
	ds_read_b128 v[118:121], v102
	s_barrier
.LBB0_174:
	s_mov_b32 s22, s49
	s_mov_b32 s54, s49
	s_cmp_ge_u32 s23, s19
	v_add_u32_e32 v249, s54, v244
	v_add_u32_e32 v212, s54, v245
	s_cbranch_scc1 .Lslow_u1e
.LBB0_185:
	s_add_i32 s100, s11, s48
	s_add_i32 s101, s11, s31
	ds_read_b128 v[126:129], v249 offset:49152
	s_waitcnt lgkmcnt(1)
	v_mfma_f32_32x32x16_bf16 v[82:97], v[98:101], v[146:149], v[66:81]
	ds_read_b128 v[122:125], v102 offset:8192
	v_mfma_f32_32x32x16_bf16 v[98:113], v[114:117], v[146:149], v[66:81]
	v_add_u32_e32 v139, s33, v241
	ds_read_b128 v[114:117], v139
	v_mfma_f32_32x32x16_bf16 v[82:97], v[118:121], v[150:153], v[82:97]
	ds_read_b128 v[118:121], v139 offset:8192
	s_waitcnt lgkmcnt(0)
	v_mfma_f32_32x32x16_bf16 v[98:113], v[122:125], v[150:153], v[98:113]
	v_add_u32_e32 v139, s33, v243
	ds_read_b128 v[122:125], v139
	v_mfma_f32_32x32x16_bf16 v[82:97], v[114:117], v[154:157], v[82:97]
	ds_read_b128 v[114:117], v139 offset:8192
	v_mfma_f32_32x32x16_bf16 v[98:113], v[118:121], v[154:157], v[98:113]
	s_waitcnt lgkmcnt(0)
	v_mfma_f32_32x32x16_bf16 v[82:97], v[122:125], v[158:161], v[82:97]
	v_mfma_f32_32x32x16_bf16 v[98:113], v[114:117], v[158:161], v[98:113]
	s_nop 0
	ds_read_b128 v[122:125], v249 offset:53248
	ds_read_b128 v[118:121], v249 offset:57344
	ds_read_b128 v[114:117], v249 offset:61440
	s_add_i32 s22, s21, 64
	s_cmp_le_u32 s22, s20
	s_cbranch_scc0 .Lnear_u1e

.LBB0_208:
	s_mov_b32 s26, s33
	s_mov_b32 s33, s31
	s_mov_b32 s31, s48
	s_mov_b32 s48, s26
	s_mov_b32 s49, s26
	v_add_u32_e32 v82, s33, v239
	v_add_u32_e32 v102, s33, v240
	ds_read_b128 v[98:101], v82
	ds_read_b128 v[114:117], v82 offset:8192
	ds_read_b128 v[118:121], v102
	s_barrier
.LBB0_214:
	s_mov_b32 s26, s49
	s_add_i32 s40, s23, 1
	s_mov_b32 s54, s49
	s_cmp_ge_u32 s40, s19
	v_add_u32_e32 v249, s54, v244
	v_add_u32_e32 v212, s54, v245
	s_cbranch_scc1 .Lslow_u1o
.LBB0_225:
	s_add_i32 s100, s11, s48
	s_add_i32 s101, s11, s31
	ds_read_b128 v[126:129], v249 offset:49152
	s_waitcnt lgkmcnt(1)
	v_mfma_f32_32x32x16_bf16 v[82:97], v[98:101], v[146:149], v[66:81]
	ds_read_b128 v[122:125], v102 offset:8192
	v_mfma_f32_32x32x16_bf16 v[98:113], v[114:117], v[146:149], v[66:81]
	v_add_u32_e32 v139, s33, v241
	ds_read_b128 v[114:117], v139
	v_mfma_f32_32x32x16_bf16 v[82:97], v[118:121], v[150:153], v[82:97]
	ds_read_b128 v[118:121], v139 offset:8192
	s_waitcnt lgkmcnt(0)
	v_mfma_f32_32x32x16_bf16 v[98:113], v[122:125], v[150:153], v[98:113]
	v_add_u32_e32 v139, s33, v243
	ds_read_b128 v[122:125], v139
	v_mfma_f32_32x32x16_bf16 v[82:97], v[114:117], v[154:157], v[82:97]
	ds_read_b128 v[114:117], v139 offset:8192
	v_mfma_f32_32x32x16_bf16 v[98:113], v[118:121], v[154:157], v[98:113]
	s_waitcnt lgkmcnt(0)
	v_mfma_f32_32x32x16_bf16 v[82:97], v[122:125], v[158:161], v[82:97]
	v_mfma_f32_32x32x16_bf16 v[98:113], v[114:117], v[158:161], v[98:113]
	s_nop 0
	ds_read_b128 v[122:125], v249 offset:53248
	ds_read_b128 v[118:121], v249 offset:57344
	ds_read_b128 v[114:117], v249 offset:61440
	s_add_i32 s26, s21, 0x80
	s_cmp_le_u32 s26, s20
	s_cbranch_scc0 .Lnear_u1o

.Lhd_u1e:
	s_add_i32 s22, s23, 2
	s_cmp_ge_u32 s22, s17
	s_cbranch_scc1 .LBB0_171
	s_mov_b32 s26, s48
	s_add_i32 s26, s11, s26
	s_add_i32 s27, s26, 0x2000
	s_mov_b32 m0, s26
	s_nop 0
	global_load_lds_dwordx4 v214, s[80:81]
	s_mov_b32 m0, s27
	s_nop 0
	global_load_lds_dwordx4 v214, s[62:63]
.LBB0_171:
	s_andn2_b64 vcc, exec, s[88:89]
	s_cbranch_vccnz .LBB0_173
	s_mov_b32 s26, s31
	s_add_i32 s26, s11, s26
	s_add_i32 m0, s26, 0xc000
	s_add_i32 s26, s26, 0xe000
	global_load_lds_dwordx4 v216, s[96:97]
	s_mov_b32 m0, s26
	s_nop 0
	global_load_lds_dwordx4 v216, s[58:59]

.Lpvo_u1e:
	s_mov_b64 s[26:27], -1
	ds_read_b128 v[98:101], v249 offset:49152
	ds_read_b128 v[114:117], v249 offset:53248
	ds_read_b128 v[130:133], v249 offset:57344
	ds_read_b128 v[194:197], v249 offset:61440
	s_waitcnt lgkmcnt(0)
	v_mfma_f32_32x32x16_bf16 v[82:97], v[98:101], v[162:165], v[34:49]
	ds_read_b128 v[206:209], v212 offset:49152
	v_mfma_f32_32x32x16_bf16 v[98:113], v[114:117], v[162:165], v[50:65]
	ds_read_b128 v[198:201], v212 offset:53248
	s_add_i32 s22, s23, 2
	s_cmp_lt_u32 s22, s17
	s_cselect_b64 s[26:27], -1, 0
	s_cmp_ge_u32 s22, s17
	s_cbranch_scc1 .LBB0_178
	s_mov_b32 s40, s48
	s_add_i32 m0, s11, s40
	s_nop 0
	global_load_lds_dwordx4 v214, s[80:81]
.LBB0_178:
	v_mfma_f32_32x32x16_bf16 v[114:129], v[130:133], v[162:165], v[18:33]
	ds_read_b128 v[202:205], v212 offset:57344
	v_mfma_f32_32x32x16_bf16 v[130:145], v[194:197], v[162:165], v[2:17]
	ds_read_b128 v[194:197], v212 offset:61440
	s_waitcnt lgkmcnt(0)
	v_mfma_f32_32x32x16_bf16 v[82:97], v[206:209], v[170:173], v[82:97]
	v_add_u32_e32 v250, s54, v246
	ds_read_b128 v[206:209], v250 offset:49152
	v_mfma_f32_32x32x16_bf16 v[98:113], v[198:201], v[170:173], v[98:113]
	ds_read_b128 v[198:201], v250 offset:53248
	s_andn2_b64 vcc, exec, s[26:27]
	s_cbranch_vccnz .LBB0_180
	s_mov_b32 s26, s48
	s_add_i32 s26, s11, s26
	s_add_i32 m0, s26, 0x2000
	s_nop 0
	global_load_lds_dwordx4 v214, s[62:63]
.LBB0_180:
	v_mfma_f32_32x32x16_bf16 v[114:129], v[202:205], v[170:173], v[114:129]
	ds_read_b128 v[202:205], v250 offset:57344
	v_mfma_f32_32x32x16_bf16 v[130:145], v[194:197], v[170:173], v[130:145]
	ds_read_b128 v[194:197], v250 offset:61440
	s_waitcnt lgkmcnt(0)
	v_mfma_f32_32x32x16_bf16 v[82:97], v[206:209], v[178:181], v[82:97]
	v_add_u32_e32 v250, s54, v247
	ds_read_b128 v[206:209], v250 offset:49152
	v_mfma_f32_32x32x16_bf16 v[98:113], v[198:201], v[178:181], v[98:113]
	ds_read_b128 v[198:201], v250 offset:53248
	v_cndmask_b32_e64 v224, 0, 1, s[88:89]
	v_cmp_ne_u32_e64 s[40:41], 1, v224
	s_andn2_b64 vcc, exec, s[88:89]
	s_cbranch_vccnz .LBB0_182
	s_mov_b32 s26, s31
	s_add_i32 s26, s11, s26
	s_add_i32 m0, s26, 0xc000
	s_nop 0
	global_load_lds_dwordx4 v216, s[96:97]
.LBB0_182:
	v_mfma_f32_32x32x16_bf16 v[114:129], v[202:205], v[178:181], v[114:129]
	ds_read_b128 v[202:205], v250 offset:57344
	v_mfma_f32_32x32x16_bf16 v[130:145], v[194:197], v[178:181], v[130:145]
	ds_read_b128 v[194:197], v250 offset:61440
	s_waitcnt lgkmcnt(0)
	v_mfma_f32_32x32x16_bf16 v[82:97], v[206:209], v[186:189], v[82:97]
	v_mfma_f32_32x32x16_bf16 v[98:113], v[198:201], v[186:189], v[98:113]
	s_and_b64 vcc, exec, s[40:41]
	s_cbranch_vccnz .LBB0_184
	s_mov_b32 s26, s31
	s_add_i32 s26, s11, s26
	s_add_i32 m0, s26, 0xe000
	s_nop 0
	global_load_lds_dwordx4 v216, s[58:59]

.Lhd_u1o:
	s_add_i32 s26, s23, 3
	s_cmp_gt_u32 s26, s16
	s_cbranch_scc1 .LBB0_211
	s_mov_b32 s26, s48
	s_add_i32 s26, s11, s26
	s_add_i32 s27, s26, 0x2000
	s_mov_b32 m0, s26
	s_nop 0
	global_load_lds_dwordx4 v214, s[50:51]
	s_mov_b32 m0, s27
	s_nop 0
	global_load_lds_dwordx4 v214, s[4:5]
.LBB0_211:
	s_andn2_b64 vcc, exec, s[88:89]
	s_cbranch_vccnz .LBB0_213
	s_mov_b32 s26, s31
	s_add_i32 s26, s11, s26
	s_add_i32 m0, s26, 0xc000
	s_add_i32 s26, s26, 0xe000
	global_load_lds_dwordx4 v216, s[0:1]
	s_mov_b32 m0, s26
	s_nop 0
	global_load_lds_dwordx4 v216, s[52:53]

.Lpvo_u1o:
	s_mov_b64 s[26:27], -1
	ds_read_b128 v[98:101], v249 offset:49152
	ds_read_b128 v[114:117], v249 offset:53248
	ds_read_b128 v[130:133], v249 offset:57344
	ds_read_b128 v[194:197], v249 offset:61440
	s_waitcnt lgkmcnt(0)
	v_mfma_f32_32x32x16_bf16 v[82:97], v[98:101], v[166:169], v[34:49]
	ds_read_b128 v[206:209], v212 offset:49152
	v_mfma_f32_32x32x16_bf16 v[98:113], v[114:117], v[166:169], v[50:65]
	ds_read_b128 v[198:201], v212 offset:53248
	s_add_i32 s40, s23, 3
	s_cmp_le_u32 s40, s16
	s_cselect_b64 s[26:27], -1, 0
	s_cmp_gt_u32 s40, s16
	s_cbranch_scc1 .LBB0_218
	s_mov_b32 s40, s48
	s_add_i32 m0, s11, s40
	s_nop 0
	global_load_lds_dwordx4 v214, s[50:51]
.LBB0_218:
	v_mfma_f32_32x32x16_bf16 v[114:129], v[130:133], v[166:169], v[18:33]
	ds_read_b128 v[202:205], v212 offset:57344
	v_mfma_f32_32x32x16_bf16 v[130:145], v[194:197], v[166:169], v[2:17]
	ds_read_b128 v[194:197], v212 offset:61440
	s_waitcnt lgkmcnt(0)
	v_mfma_f32_32x32x16_bf16 v[82:97], v[206:209], v[174:177], v[82:97]
	v_add_u32_e32 v250, s54, v246
	ds_read_b128 v[206:209], v250 offset:49152
	v_mfma_f32_32x32x16_bf16 v[98:113], v[198:201], v[174:177], v[98:113]
	ds_read_b128 v[198:201], v250 offset:53248
	s_andn2_b64 vcc, exec, s[26:27]
	s_cbranch_vccnz .LBB0_220
	s_mov_b32 s26, s48
	s_add_i32 s26, s11, s26
	s_add_i32 m0, s26, 0x2000
	s_nop 0
	global_load_lds_dwordx4 v214, s[4:5]
.LBB0_220:
	v_mfma_f32_32x32x16_bf16 v[114:129], v[202:205], v[174:177], v[114:129]
	ds_read_b128 v[202:205], v250 offset:57344
	v_mfma_f32_32x32x16_bf16 v[130:145], v[194:197], v[174:177], v[130:145]
	ds_read_b128 v[194:197], v250 offset:61440
	s_waitcnt lgkmcnt(0)
	v_mfma_f32_32x32x16_bf16 v[82:97], v[206:209], v[182:185], v[82:97]
	v_add_u32_e32 v250, s54, v247
	ds_read_b128 v[206:209], v250 offset:49152
	v_mfma_f32_32x32x16_bf16 v[98:113], v[198:201], v[182:185], v[98:113]
	ds_read_b128 v[198:201], v250 offset:53248
	v_cndmask_b32_e64 v224, 0, 1, s[88:89]
	v_cmp_ne_u32_e64 s[40:41], 1, v224
	s_andn2_b64 vcc, exec, s[88:89]
	s_cbranch_vccnz .LBB0_222
	s_mov_b32 s26, s31
	s_add_i32 s26, s11, s26
	s_add_i32 m0, s26, 0xc000
	s_nop 0
	global_load_lds_dwordx4 v216, s[0:1]
.LBB0_222:
	v_mfma_f32_32x32x16_bf16 v[114:129], v[202:205], v[182:185], v[114:129]
	ds_read_b128 v[202:205], v250 offset:57344
	v_mfma_f32_32x32x16_bf16 v[130:145], v[194:197], v[182:185], v[130:145]
	ds_read_b128 v[194:197], v250 offset:61440
	s_waitcnt lgkmcnt(0)
	v_mfma_f32_32x32x16_bf16 v[82:97], v[206:209], v[190:193], v[82:97]
	v_mfma_f32_32x32x16_bf16 v[98:113], v[198:201], v[190:193], v[98:113]
	s_and_b64 vcc, exec, s[40:41]
	s_cbranch_vccnz .LBB0_224
	s_mov_b32 s26, s31
	s_add_i32 s26, s11, s26
	s_add_i32 m0, s26, 0xe000
	s_nop 0
	global_load_lds_dwordx4 v216, s[52:53]

.LBB0_266:
	s_nop 6
	v_max_f32_e32 v0, v19, v19
	v_max_f32_e32 v39, v3, v3
	v_max_f32_e32 v0, v39, v0
	v_max3_f32 v0, v2, v18, v0
	v_max3_f32 v39, v20, v5, v21
	v_max3_f32 v0, v0, v4, v39
	v_max3_f32 v39, v22, v7, v23
	v_max3_f32 v0, v0, v6, v39
	v_max3_f32 v39, v24, v9, v25
	v_max3_f32 v0, v0, v8, v39
	v_max3_f32 v39, v26, v11, v27
	v_max3_f32 v0, v0, v10, v39
	v_max3_f32 v39, v28, v13, v29
	v_max3_f32 v0, v0, v12, v39
	v_max3_f32 v39, v30, v15, v31
	v_max3_f32 v0, v0, v14, v39
	v_max3_f32 v39, v32, v17, v33
	v_max3_f32 v0, v0, v16, v39
	v_mov_b32_e32 v39, v0
	s_nop 1
	v_permlane32_swap_b32_e32 v0, v39
	v_max_f32_e32 v39, v39, v39
	v_max_f32_e32 v0, v0, v0
	v_max_f32_e32 v213, v0, v39
	v_sub_f32_e32 v0, v2, v213
	v_exp_f32_e32 v40, v0
	v_sub_f32_e32 v0, v18, v213
	v_exp_f32_e32 v41, v0
	v_sub_f32_e32 v0, v3, v213
	v_sub_f32_e32 v2, v19, v213
	v_exp_f32_e32 v0, v0
	v_exp_f32_e32 v2, v2
	v_add_f32_e32 v3, v41, v40
	s_movk_i32 s27, 0x510
	v_cvt_pk_bf16_f32 v162, v40, v0
	v_pk_add_f32 v[18:19], v[2:3], v[0:1]
	v_sub_f32_e32 v3, v4, v213
	v_sub_f32_e32 v4, v20, v213
	v_pk_add_f32 v[18:19], v[18:19], v[18:19] op_sel_hi:[0,1]
	v_exp_f32_e32 v43, v4
	v_sub_f32_e32 v4, v5, v213
	v_exp_f32_e32 v3, v3
	v_exp_f32_e32 v18, v4
	v_sub_f32_e32 v4, v21, v213
	v_exp_f32_e32 v4, v4
	v_add_f32_e32 v5, v43, v3
	v_xad_u32 v0, v37, -1, v236
	v_cvt_pk_bf16_f32 v178, v41, v2
	v_pk_add_f32 v[20:21], v[4:5], v[18:19]
	v_sub_f32_e32 v5, v6, v213
	v_sub_f32_e32 v6, v22, v213
	v_pk_add_f32 v[20:21], v[20:21], v[20:21] op_sel_hi:[0,1]
	v_exp_f32_e32 v19, v6
	v_sub_f32_e32 v6, v7, v213
	v_exp_f32_e32 v5, v5
	v_exp_f32_e32 v20, v6
	v_sub_f32_e32 v6, v23, v213
	v_exp_f32_e32 v6, v6
	v_add_f32_e32 v7, v19, v5
	v_and_b32_e32 v0, 3, v0
	v_mov_b32_e32 v2, s31
	v_pk_add_f32 v[22:23], v[6:7], v[20:21]
	v_sub_f32_e32 v7, v8, v213
	v_sub_f32_e32 v8, v24, v213
	v_pk_add_f32 v[22:23], v[22:23], v[22:23] op_sel_hi:[0,1]
	v_exp_f32_e32 v21, v8
	v_sub_f32_e32 v8, v9, v213
	v_exp_f32_e32 v7, v7
	v_exp_f32_e32 v22, v8
	v_sub_f32_e32 v8, v25, v213
	v_exp_f32_e32 v8, v8
	v_add_f32_e32 v9, v21, v7
	s_add_i32 s20, s20, s56
	v_mad_u32_u24 v244, v0, s27, v2
	v_pk_add_f32 v[24:25], v[8:9], v[22:23]
	v_sub_f32_e32 v9, v10, v213
	v_sub_f32_e32 v10, v26, v213
	v_pk_add_f32 v[24:25], v[24:25], v[24:25] op_sel_hi:[0,1]
	v_exp_f32_e32 v23, v10
	v_sub_f32_e32 v10, v11, v213
	v_exp_f32_e32 v9, v9
	v_exp_f32_e32 v24, v10
	v_sub_f32_e32 v10, v27, v213
	v_exp_f32_e32 v10, v10
	v_add_f32_e32 v11, v23, v9
	v_add_u32_e32 v2, s20, v233
	v_cvt_pk_bf16_f32 v163, v3, v18
	v_pk_add_f32 v[26:27], v[10:11], v[24:25]
	v_sub_f32_e32 v11, v12, v213
	v_sub_f32_e32 v12, v28, v213
	v_pk_add_f32 v[26:27], v[26:27], v[26:27] op_sel_hi:[0,1]
	v_exp_f32_e32 v25, v12
	v_sub_f32_e32 v12, v13, v213
	v_exp_f32_e32 v11, v11
	v_exp_f32_e32 v26, v12
	v_sub_f32_e32 v12, v29, v213
	v_exp_f32_e32 v12, v12
	v_add_f32_e32 v13, v25, v11
	v_ashrrev_i32_e32 v3, 31, v2
	v_lshlrev_b64 v[2:3], 12, v[2:3]
	v_pk_add_f32 v[28:29], v[12:13], v[26:27]
	v_sub_f32_e32 v13, v14, v213
	v_sub_f32_e32 v14, v30, v213
	v_pk_add_f32 v[28:29], v[28:29], v[28:29] op_sel_hi:[0,1]
	v_exp_f32_e32 v27, v14
	v_sub_f32_e32 v14, v15, v213
	v_exp_f32_e32 v13, v13
	v_exp_f32_e32 v28, v14
	v_sub_f32_e32 v14, v31, v213
	v_exp_f32_e32 v14, v14
	v_sub_f32_e32 v15, v16, v213
	v_exp_f32_e32 v48, v15
	v_sub_f32_e32 v15, v32, v213
	v_exp_f32_e32 v32, v15
	v_add_f32_e32 v15, v27, v13
	v_pk_add_f32 v[30:31], v[14:15], v[28:29]
	v_and_b32_e32 v0, 15, v34
	v_pk_add_f32 v[30:31], v[30:31], v[30:31] op_sel_hi:[0,1]
	v_sub_f32_e32 v15, v17, v213
	v_or_b32_e32 v2, s37, v2
	v_lshlrev_b32_e32 v0, 4, v0
	s_add_i32 s21, s21, s36
	v_exp_f32_e32 v30, v15
	v_sub_f32_e32 v15, v33, v213
	v_lshl_add_u64 v[214:215], v[2:3], 0, v[0:1]
	v_add_u32_e32 v2, s21, v36
	v_and_b32_e32 v39, 7, v38
	v_bitop3_b32 v44, v38, v234, 7 bitop3:0x6c
	v_exp_f32_e32 v38, v15
	v_ashrrev_i32_e32 v3, 31, v2
	v_lshlrev_b64 v[2:3], 15, v[2:3]
	v_and_b32_e32 v0, 7, v35
	s_and_b32 s26, s47, 15
	v_lshl_or_b32 v2, v0, 4, v2
	v_sub_u32_e32 v0, v236, v235
	v_lshlrev_b32_e32 v42, 7, v235
	v_bitop3_b32 v45, v234, v39, 2 bitop3:0x36
	v_bitop3_b32 v46, v234, v39, 4 bitop3:0x36
	v_bitop3_b32 v47, v234, v39, 6 bitop3:0x36
	s_lshl_b32 s26, s26, 7
	v_add_f32_e32 v39, v32, v48
	v_cvt_pk_bf16_f32 v188, v27, v14
	v_subrev_u32_e32 v0, s28, v0
	v_mov_b32_e32 v14, v1
	v_mov_b32_e32 v15, v1
	s_lshl_b32 s17, s46, 1
	s_lshr_b32 s19, s16, 6
	v_pk_add_f32 v[16:17], v[38:39], v[30:31]
	v_cvt_pk_bf16_f32 v164, v5, v20
	v_cvt_pk_bf16_f32 v165, v7, v22
	v_cvt_pk_bf16_f32 v170, v9, v24
	v_cvt_pk_bf16_f32 v171, v11, v26
	v_cvt_pk_bf16_f32 v172, v13, v28
	v_cvt_pk_bf16_f32 v173, v48, v30
	v_cvt_pk_bf16_f32 v179, v43, v4
	v_cvt_pk_bf16_f32 v180, v19, v6
	v_cvt_pk_bf16_f32 v181, v21, v8
	v_cvt_pk_bf16_f32 v186, v23, v10
	v_cvt_pk_bf16_f32 v187, v25, v12
	v_cvt_pk_bf16_f32 v189, v32, v38
	v_lshl_or_b32 v245, v44, 4, v42
	v_lshl_or_b32 v246, v45, 4, v42
	v_lshl_or_b32 v247, v46, 4, v42
	v_lshl_or_b32 v248, v47, 4, v42
	v_lshl_add_u64 v[216:217], v[2:3], 0, s[44:45]
	v_subrev_u32_e32 v249, s26, v0
	v_mov_b32_e32 v0, v1
	v_mov_b32_e32 v2, v1
	v_mov_b32_e32 v3, v1
	v_mov_b32_e32 v4, v1
	v_mov_b32_e32 v5, v1
	v_mov_b32_e32 v6, v1
	v_mov_b32_e32 v7, v1
	v_mov_b32_e32 v8, v1
	v_mov_b32_e32 v9, v1
	v_mov_b32_e32 v10, v1
	v_mov_b32_e32 v11, v1
	v_mov_b32_e32 v12, v1
	v_mov_b32_e32 v13, v1
	v_mov_b64_e32 v[64:65], v[14:15]
	v_mov_b64_e32 v[48:49], v[14:15]
	v_mov_b64_e32 v[32:33], v[14:15]
	s_add_i32 s18, s17, 2
	s_add_i32 s19, s19, 1
	v_xor_b32_e32 v66, 0x80000000, v213
	v_add_f32_e32 v243, v16, v17
	v_mov_b64_e32 v[62:63], v[12:13]
	v_mov_b64_e32 v[60:61], v[10:11]
	v_mov_b64_e32 v[58:59], v[8:9]
	v_mov_b64_e32 v[56:57], v[6:7]
	v_mov_b64_e32 v[54:55], v[4:5]
	v_mov_b64_e32 v[52:53], v[2:3]
	v_mov_b64_e32 v[50:51], v[0:1]
	v_mov_b64_e32 v[46:47], v[12:13]
	v_mov_b64_e32 v[44:45], v[10:11]
	v_mov_b64_e32 v[42:43], v[8:9]
	v_mov_b64_e32 v[40:41], v[6:7]
	v_mov_b64_e32 v[38:39], v[4:5]
	v_mov_b64_e32 v[36:37], v[2:3]
	v_mov_b64_e32 v[34:35], v[0:1]
	v_mov_b64_e32 v[30:31], v[12:13]
	v_mov_b64_e32 v[28:29], v[10:11]
	v_mov_b64_e32 v[26:27], v[8:9]
	v_mov_b64_e32 v[24:25], v[6:7]
	v_mov_b64_e32 v[22:23], v[4:5]
	v_mov_b64_e32 v[20:21], v[2:3]
	v_mov_b64_e32 v[18:19], v[0:1]
	v_mov_b64_e32 v[16:17], v[14:15]
	s_mov_b32 s22, 1
	s_mov_b32 s23, 0x8000
	s_min_u32 s19, s18, s19
	v_mov_b32_e32 v67, v66
	v_mov_b32_e32 v68, v66
	v_mov_b32_e32 v69, v66
	v_mov_b32_e32 v70, v66
	v_mov_b32_e32 v71, v66
	v_mov_b32_e32 v72, v66
	v_mov_b32_e32 v73, v66
	v_mov_b32_e32 v74, v66
	v_mov_b32_e32 v75, v66
	v_mov_b32_e32 v76, v66
	v_mov_b32_e32 v77, v66
	v_mov_b32_e32 v78, v66
	v_mov_b32_e32 v79, v66
	v_mov_b32_e32 v80, v66
	v_mov_b32_e32 v81, v66
	s_mov_b32 s28, 0
	s_movk_i32 s20, 0xf0
	v_mov_b32_e32 v166, 0
	v_mov_b32_e32 v167, 0
	v_mov_b32_e32 v168, 0
	v_mov_b32_e32 v169, 0
	v_mov_b32_e32 v174, 0
	v_mov_b32_e32 v175, 0
	v_mov_b32_e32 v176, 0
	v_mov_b32_e32 v177, 0
	v_mov_b32_e32 v182, 0
	v_mov_b32_e32 v183, 0
	v_mov_b32_e32 v184, 0
	v_mov_b32_e32 v185, 0
	v_mov_b32_e32 v190, 0
	v_mov_b32_e32 v191, 0
	v_mov_b32_e32 v192, 0
	v_mov_b32_e32 v193, 0
	v_mov_b64_e32 v[14:15], v[12:13]
	v_mov_b64_e32 v[12:13], v[10:11]
	v_mov_b64_e32 v[10:11], v[8:9]
	v_mov_b64_e32 v[8:9], v[6:7]
	v_mov_b64_e32 v[6:7], v[4:5]
	v_mov_b64_e32 v[4:5], v[2:3]
	v_mov_b64_e32 v[2:3], v[0:1]
	s_mov_b32 s31, 0x4000
	s_mov_b32 s33, 0

.LBB0_271:
	v_add_u32_e32 v82, s31, v239
	v_add_u32_e32 v102, s31, v240
	ds_read_b128 v[98:101], v82
	ds_read_b128 v[114:117], v82 offset:8192
	ds_read_b128 v[118:121], v102
	s_barrier
.LBB0_277:
	s_mov_b32 s21, s33
	s_mov_b32 s36, s33
	s_cmp_ge_u32 s22, s19
	v_add_u32_e32 v212, s36, v245
	v_add_u32_e32 v0, s36, v246
	s_cbranch_scc1 .Lslow_u2e
.LBB0_288:
	s_add_i32 s100, s10, s28
	s_add_i32 s101, s10, s23
	ds_read_b128 v[126:129], v212 offset:49152
	s_waitcnt lgkmcnt(1)
	v_mfma_f32_32x32x16_bf16 v[82:97], v[98:101], v[146:149], v[66:81]
	ds_read_b128 v[122:125], v102 offset:8192
	v_mfma_f32_32x32x16_bf16 v[98:113], v[114:117], v[146:149], v[66:81]
	v_add_u32_e32 v139, s31, v241
	ds_read_b128 v[114:117], v139
	v_mfma_f32_32x32x16_bf16 v[82:97], v[118:121], v[150:153], v[82:97]
	ds_read_b128 v[118:121], v139 offset:8192
	s_waitcnt lgkmcnt(0)
	v_mfma_f32_32x32x16_bf16 v[98:113], v[122:125], v[150:153], v[98:113]
	v_add_u32_e32 v139, s31, v242
	ds_read_b128 v[122:125], v139
	v_mfma_f32_32x32x16_bf16 v[82:97], v[114:117], v[154:157], v[82:97]
	ds_read_b128 v[114:117], v139 offset:8192
	v_mfma_f32_32x32x16_bf16 v[98:113], v[118:121], v[154:157], v[98:113]
	s_waitcnt lgkmcnt(0)
	v_mfma_f32_32x32x16_bf16 v[82:97], v[122:125], v[158:161], v[82:97]
	v_mfma_f32_32x32x16_bf16 v[98:113], v[114:117], v[158:161], v[98:113]
	s_nop 0
	ds_read_b128 v[122:125], v212 offset:53248
	ds_read_b128 v[118:121], v212 offset:57344
	ds_read_b128 v[114:117], v212 offset:61440
	s_cmp_le_u32 s20, s16
	s_cbranch_scc0 .Lnear_u2e

.LBB0_311:
	s_mov_b32 s26, s31
	s_mov_b32 s31, s23
	s_mov_b32 s23, s28
	s_mov_b32 s28, s26
	s_mov_b32 s33, s26
	v_add_u32_e32 v82, s31, v239
	v_add_u32_e32 v102, s31, v240
	ds_read_b128 v[98:101], v82
	ds_read_b128 v[114:117], v82 offset:8192
	ds_read_b128 v[118:121], v102
	s_barrier
.LBB0_317:
	s_mov_b32 s26, s33
	s_add_i32 s37, s22, 1
	s_mov_b32 s36, s33
	s_cmp_ge_u32 s37, s19
	v_add_u32_e32 v212, s36, v245
	v_add_u32_e32 v0, s36, v246
	s_cbranch_scc1 .Lslow_u2o
.LBB0_328:
	s_add_i32 s100, s10, s28
	s_add_i32 s101, s10, s23
	ds_read_b128 v[126:129], v212 offset:49152
	s_waitcnt lgkmcnt(1)
	v_mfma_f32_32x32x16_bf16 v[82:97], v[98:101], v[146:149], v[66:81]
	ds_read_b128 v[122:125], v102 offset:8192
	v_mfma_f32_32x32x16_bf16 v[98:113], v[114:117], v[146:149], v[66:81]
	v_add_u32_e32 v139, s31, v241
	ds_read_b128 v[114:117], v139
	v_mfma_f32_32x32x16_bf16 v[82:97], v[118:121], v[150:153], v[82:97]
	ds_read_b128 v[118:121], v139 offset:8192
	s_waitcnt lgkmcnt(0)
	v_mfma_f32_32x32x16_bf16 v[98:113], v[122:125], v[150:153], v[98:113]
	v_add_u32_e32 v139, s31, v242
	ds_read_b128 v[122:125], v139
	v_mfma_f32_32x32x16_bf16 v[82:97], v[114:117], v[154:157], v[82:97]
	ds_read_b128 v[114:117], v139 offset:8192
	v_mfma_f32_32x32x16_bf16 v[98:113], v[118:121], v[154:157], v[98:113]
	s_waitcnt lgkmcnt(0)
	v_mfma_f32_32x32x16_bf16 v[82:97], v[122:125], v[158:161], v[82:97]
	v_mfma_f32_32x32x16_bf16 v[98:113], v[114:117], v[158:161], v[98:113]
	s_nop 0
	ds_read_b128 v[122:125], v212 offset:53248
	ds_read_b128 v[118:121], v212 offset:57344
	ds_read_b128 v[114:117], v212 offset:61440
	s_add_i32 s26, s20, 64
	s_cmp_le_u32 s26, s16
	s_cbranch_scc0 .Lnear_u2o

.Lhd_u2e:
	s_add_i32 s21, s22, 2
	s_cmp_ge_u32 s21, s18
	s_cbranch_scc1 .LBB0_274
	s_mov_b32 s26, s28
	s_add_i32 s26, s10, s26
	s_add_i32 s27, s26, 0x2000
	s_mov_b32 m0, s26
	s_nop 0
	global_load_lds_dwordx4 v214, s[80:81]
	s_mov_b32 m0, s27
	s_nop 0
	global_load_lds_dwordx4 v214, s[62:63]
.LBB0_274:
	s_andn2_b64 vcc, exec, s[44:45]
	s_cbranch_vccnz .LBB0_276
	s_mov_b32 s26, s23
	s_add_i32 s26, s10, s26
	s_add_i32 m0, s26, 0xc000
	s_add_i32 s26, s26, 0xe000
	global_load_lds_dwordx4 v216, s[96:97]
	s_mov_b32 m0, s26
	s_nop 0
	global_load_lds_dwordx4 v216, s[58:59]

.Lpvo_u2e:
	s_mov_b64 s[26:27], -1
	ds_read_b128 v[98:101], v212 offset:49152
	ds_read_b128 v[114:117], v212 offset:53248
	ds_read_b128 v[130:133], v212 offset:57344
	ds_read_b128 v[194:197], v212 offset:61440
	s_waitcnt lgkmcnt(0)
	v_mfma_f32_32x32x16_bf16 v[82:97], v[98:101], v[162:165], v[50:65]
	ds_read_b128 v[206:209], v0 offset:49152
	v_mfma_f32_32x32x16_bf16 v[98:113], v[114:117], v[162:165], v[34:49]
	ds_read_b128 v[198:201], v0 offset:53248
	s_add_i32 s21, s22, 2
	s_cmp_lt_u32 s21, s18
	s_cselect_b64 s[26:27], -1, 0
	s_cmp_ge_u32 s21, s18
	s_cbranch_scc1 .LBB0_281
	s_mov_b32 s37, s28
	s_add_i32 m0, s10, s37
	s_nop 0
	global_load_lds_dwordx4 v214, s[80:81]
.LBB0_281:
	v_mfma_f32_32x32x16_bf16 v[114:129], v[130:133], v[162:165], v[18:33]
	ds_read_b128 v[202:205], v0 offset:57344
	v_mfma_f32_32x32x16_bf16 v[130:145], v[194:197], v[162:165], v[2:17]
	ds_read_b128 v[194:197], v0 offset:61440
	s_waitcnt lgkmcnt(0)
	v_mfma_f32_32x32x16_bf16 v[82:97], v[206:209], v[170:173], v[82:97]
	v_add_u32_e32 v250, s36, v247
	ds_read_b128 v[206:209], v250 offset:49152
	v_mfma_f32_32x32x16_bf16 v[98:113], v[198:201], v[170:173], v[98:113]
	ds_read_b128 v[198:201], v250 offset:53248
	s_andn2_b64 vcc, exec, s[26:27]
	s_cbranch_vccnz .LBB0_283
	s_mov_b32 s26, s28
	s_add_i32 s26, s10, s26
	s_add_i32 m0, s26, 0x2000
	s_nop 0
	global_load_lds_dwordx4 v214, s[62:63]
.LBB0_283:
	v_mfma_f32_32x32x16_bf16 v[114:129], v[202:205], v[170:173], v[114:129]
	ds_read_b128 v[202:205], v250 offset:57344
	v_mfma_f32_32x32x16_bf16 v[130:145], v[194:197], v[170:173], v[130:145]
	ds_read_b128 v[194:197], v250 offset:61440
	s_waitcnt lgkmcnt(0)
	v_mfma_f32_32x32x16_bf16 v[82:97], v[206:209], v[178:181], v[82:97]
	v_add_u32_e32 v250, s36, v248
	ds_read_b128 v[206:209], v250 offset:49152
	v_mfma_f32_32x32x16_bf16 v[98:113], v[198:201], v[178:181], v[98:113]
	ds_read_b128 v[198:201], v250 offset:53248
	v_cndmask_b32_e64 v224, 0, 1, s[44:45]
	v_cmp_ne_u32_e64 s[40:41], 1, v224
	s_andn2_b64 vcc, exec, s[44:45]
	s_cbranch_vccnz .LBB0_285
	s_mov_b32 s26, s23
	s_add_i32 s26, s10, s26
	s_add_i32 m0, s26, 0xc000
	s_nop 0
	global_load_lds_dwordx4 v216, s[96:97]
.LBB0_285:
	v_mfma_f32_32x32x16_bf16 v[114:129], v[202:205], v[178:181], v[114:129]
	ds_read_b128 v[202:205], v250 offset:57344
	v_mfma_f32_32x32x16_bf16 v[130:145], v[194:197], v[178:181], v[130:145]
	ds_read_b128 v[194:197], v250 offset:61440
	s_waitcnt lgkmcnt(0)
	v_mfma_f32_32x32x16_bf16 v[82:97], v[206:209], v[186:189], v[82:97]
	v_mfma_f32_32x32x16_bf16 v[98:113], v[198:201], v[186:189], v[98:113]
	s_and_b64 vcc, exec, s[40:41]
	s_cbranch_vccnz .LBB0_287
	s_mov_b32 s26, s23
	s_add_i32 s26, s10, s26
	s_add_i32 m0, s26, 0xe000
	s_nop 0
	global_load_lds_dwordx4 v216, s[58:59]

.Lhd_u2o:
	s_add_i32 s26, s22, 3
	s_cmp_gt_u32 s26, s17
	s_cbranch_scc1 .LBB0_314
	s_mov_b32 s26, s28
	s_add_i32 s26, s10, s26
	s_add_i32 s27, s26, 0x2000
	s_mov_b32 m0, s26
	s_nop 0
	global_load_lds_dwordx4 v214, s[50:51]
	s_mov_b32 m0, s27
	s_nop 0
	global_load_lds_dwordx4 v214, s[4:5]
.LBB0_314:
	s_andn2_b64 vcc, exec, s[44:45]
	s_cbranch_vccnz .LBB0_316
	s_mov_b32 s26, s23
	s_add_i32 s26, s10, s26
	s_add_i32 m0, s26, 0xc000
	s_add_i32 s26, s26, 0xe000
	global_load_lds_dwordx4 v216, s[0:1]
	s_mov_b32 m0, s26
	s_nop 0
	global_load_lds_dwordx4 v216, s[52:53]

.Lpvo_u2o:
	s_mov_b64 s[26:27], -1
	ds_read_b128 v[98:101], v212 offset:49152
	ds_read_b128 v[114:117], v212 offset:53248
	ds_read_b128 v[130:133], v212 offset:57344
	ds_read_b128 v[194:197], v212 offset:61440
	s_waitcnt lgkmcnt(0)
	v_mfma_f32_32x32x16_bf16 v[82:97], v[98:101], v[166:169], v[50:65]
	ds_read_b128 v[206:209], v0 offset:49152
	v_mfma_f32_32x32x16_bf16 v[98:113], v[114:117], v[166:169], v[34:49]
	ds_read_b128 v[198:201], v0 offset:53248
	s_add_i32 s37, s22, 3
	s_cmp_le_u32 s37, s17
	s_cselect_b64 s[26:27], -1, 0
	s_cmp_gt_u32 s37, s17
	s_cbranch_scc1 .LBB0_321
	s_mov_b32 s37, s28
	s_add_i32 m0, s10, s37
	s_nop 0
	global_load_lds_dwordx4 v214, s[50:51]
.LBB0_321:
	v_mfma_f32_32x32x16_bf16 v[114:129], v[130:133], v[166:169], v[18:33]
	ds_read_b128 v[202:205], v0 offset:57344
	v_mfma_f32_32x32x16_bf16 v[130:145], v[194:197], v[166:169], v[2:17]
	ds_read_b128 v[194:197], v0 offset:61440
	s_waitcnt lgkmcnt(0)
	v_mfma_f32_32x32x16_bf16 v[82:97], v[206:209], v[174:177], v[82:97]
	v_add_u32_e32 v250, s36, v247
	ds_read_b128 v[206:209], v250 offset:49152
	v_mfma_f32_32x32x16_bf16 v[98:113], v[198:201], v[174:177], v[98:113]
	ds_read_b128 v[198:201], v250 offset:53248
	s_andn2_b64 vcc, exec, s[26:27]
	s_cbranch_vccnz .LBB0_323
	s_mov_b32 s26, s28
	s_add_i32 s26, s10, s26
	s_add_i32 m0, s26, 0x2000
	s_nop 0
	global_load_lds_dwordx4 v214, s[4:5]
.LBB0_323:
	v_mfma_f32_32x32x16_bf16 v[114:129], v[202:205], v[174:177], v[114:129]
	ds_read_b128 v[202:205], v250 offset:57344
	v_mfma_f32_32x32x16_bf16 v[130:145], v[194:197], v[174:177], v[130:145]
	ds_read_b128 v[194:197], v250 offset:61440
	s_waitcnt lgkmcnt(0)
	v_mfma_f32_32x32x16_bf16 v[82:97], v[206:209], v[182:185], v[82:97]
	v_add_u32_e32 v250, s36, v248
	ds_read_b128 v[206:209], v250 offset:49152
	v_mfma_f32_32x32x16_bf16 v[98:113], v[198:201], v[182:185], v[98:113]
	ds_read_b128 v[198:201], v250 offset:53248
	v_cndmask_b32_e64 v224, 0, 1, s[44:45]
	v_cmp_ne_u32_e64 s[40:41], 1, v224
	s_andn2_b64 vcc, exec, s[44:45]
	s_cbranch_vccnz .LBB0_325
	s_mov_b32 s26, s23
	s_add_i32 s26, s10, s26
	s_add_i32 m0, s26, 0xc000
	s_nop 0
	global_load_lds_dwordx4 v216, s[0:1]
.LBB0_325:
	v_mfma_f32_32x32x16_bf16 v[114:129], v[202:205], v[182:185], v[114:129]
	ds_read_b128 v[202:205], v250 offset:57344
	v_mfma_f32_32x32x16_bf16 v[130:145], v[194:197], v[182:185], v[130:145]
	ds_read_b128 v[194:197], v250 offset:61440
	s_waitcnt lgkmcnt(0)
	v_mfma_f32_32x32x16_bf16 v[82:97], v[206:209], v[190:193], v[82:97]
	v_mfma_f32_32x32x16_bf16 v[98:113], v[198:201], v[190:193], v[98:113]
	s_and_b64 vcc, exec, s[40:41]
	s_cbranch_vccnz .LBB0_327
	s_mov_b32 s26, s23
	s_add_i32 s26, s10, s26
	s_add_i32 m0, s26, 0xe000
	s_nop 0
	global_load_lds_dwordx4 v216, s[52:53]
